# P5 tail round: 4 K-slices of 512 instead of 8 of 256 (half the f32 partial traffic), fix-up sums 4 partials
# speedup vs baseline: 1.0027x; 1.0005x over previous
.LBB0_1068:
	s_cmp_eq_u32 s36, 0
	s_cbranch_scc1 .LBB0_1156
	s_add_u32 s10, s96, 0x14ec0000
	s_addc_u32 s11, s97, 0
	s_lshl_b32 s7, s36, 3
	s_cmp_lt_i32 s88, s7
	s_cselect_b64 s[12:13], -1, 0
	s_lshl_b32 s98, s36, 2
	s_cmp_ge_i32 s88, s98
	v_readfirstlane_b32 s0, v208
	s_cbranch_scc1 .LBB0_1089
	s_ashr_i32 s3, s88, 31
	s_lshr_b32 s3, s3, 30
	s_add_i32 s3, s88, s3
	s_ashr_i32 s14, s3, 2
	s_add_i32 s14, s6, s14
	s_ashr_i32 s15, s14, 31
	s_lshr_b32 s15, s15, 29
	s_add_i32 s15, s14, s15
	s_lshr_b32 s1, s0, 6
	s_ashr_i32 s17, s15, 3
	s_and_b32 s15, s15, -8
	s_lshr_b32 s16, s0, 8
	s_lshl_b32 s2, s1, 10
	s_sub_i32 s14, s14, s15
	s_cmp_lt_i32 s14, 0
	s_cselect_b32 s15, 36, 35
	s_mul_i32 s14, s14, s15
	s_add_i32 s14, s14, s17
	s_ashr_i32 s15, s14, 31
	s_lshr_b32 s15, s15, 27
	s_add_i32 s15, s14, s15
	s_ashr_i32 s17, s15, 5
	s_lshl_b32 s17, s17, 2
	s_sub_i32 s18, 35, s17
	s_min_i32 s18, s18, 4
	s_abs_i32 s19, s18
	v_cvt_f32_u32_e32 v0, s19
	s_sub_i32 s21, 0, s19
	s_andn2_b32 s15, s15, 31
	s_sub_i32 s15, s14, s15
	v_rcp_iflag_f32_e32 v0, v0
	s_abs_i32 s20, s15
	s_xor_b32 s14, s15, s18
	s_ashr_i32 s14, s14, 31
	v_mul_f32_e32 v0, 0x4f7ffffe, v0
	v_cvt_u32_f32_e32 v0, v0
	v_mov_b32_e32 v141, 0
	v_mov_b32_e32 v145, v141
	v_mov_b32_e32 v139, v141
	v_readfirstlane_b32 s22, v0
	s_mul_i32 s21, s21, s22
	s_mul_hi_u32 s21, s22, s21
	s_add_i32 s22, s22, s21
	s_mul_hi_u32 s21, s20, s22
	s_mul_i32 s22, s21, s19
	s_sub_i32 s20, s20, s22
	s_add_i32 s22, s21, 1
	s_sub_i32 s23, s20, s19
	s_cmp_ge_u32 s20, s19
	s_cselect_b32 s21, s22, s21
	s_cselect_b32 s20, s23, s20
	s_add_i32 s22, s21, 1
	s_cmp_ge_u32 s20, s19
	s_cselect_b32 s19, s22, s21
	s_xor_b32 s19, s19, s14
	s_sub_i32 s14, s19, s14
	s_mul_i32 s18, s14, s18
	s_sub_i32 s15, s15, s18
	s_and_b32 s3, s3, -4
	s_add_i32 s18, s17, s15
	s_sub_i32 s20, s88, s3
	s_ashr_i32 s19, s18, 31
	s_ashr_i32 s21, s20, 31
	s_ashr_i32 s15, s14, 31
	s_lshl_b64 s[18:19], s[18:19], 20
	s_lshl_b64 s[20:21], s[20:21], 10
	s_lshl_b64 s[14:15], s[14:15], 20
	s_add_u32 s3, s54, s14
	s_addc_u32 s14, s55, s15
	s_add_u32 s26, s3, s20
	s_addc_u32 s27, s14, s21
	s_add_i32 s3, s2, 0
	s_add_i32 m0, s3, 0x10000
	v_mov_b32_e32 v143, v141
	global_load_lds_dwordx4 v140, s[26:27]
	s_add_i32 m0, s3, 0x12000
	s_add_u32 s17, s52, s18
	s_addc_u32 s18, s53, s19
	s_add_u32 s14, s26, 0x80000
	global_load_lds_dwordx4 v144, s[26:27]
	s_addc_u32 s15, s27, 0
	s_add_i32 m0, s3, 0x14000
	s_mov_b64 s[82:83], s[62:63]
	global_load_lds_dwordx4 v140, s[14:15]
	s_add_i32 m0, s3, 0x16000
	s_add_u32 s30, s17, s20
	s_addc_u32 s31, s18, s21
	s_add_i32 s56, s3, 0x2000
	global_load_lds_dwordx4 v144, s[14:15]
	s_mov_b32 m0, s3
	s_add_u32 s14, s30, 0x80000
	global_load_lds_dwordx4 v138, s[30:31]
	s_mov_b32 m0, s56
	s_addc_u32 s15, s31, 0
	s_add_i32 s57, s3, 0x4000
	global_load_lds_dwordx4 v142, s[30:31]
	s_mov_b32 m0, s57
	s_add_i32 s58, s3, 0x6000
	global_load_lds_dwordx4 v138, s[14:15]
	s_mov_b32 m0, s58
	s_cmp_eq_u32 s16, 1
	global_load_lds_dwordx4 v142, s[14:15]
	s_mov_b32 s78, s61
	s_mov_b32 s59, 0
	v_lshl_add_u64 v[4:5], s[26:27], 0, v[140:141]
	v_lshl_add_u64 v[0:1], s[26:27], 0, v[144:145]
	v_lshl_add_u64 v[2:3], s[30:31], 0, v[138:139]
	s_cselect_b64 s[14:15], -1, 0
	s_cmp_lg_u32 s16, 1
	v_lshl_add_u64 v[6:7], s[30:31], 0, v[142:143]
	s_cbranch_scc1 .LBB0_1072
	s_barrier

.LBB0_1081:
	v_mov_b32_e32 v0, 0
	s_mov_b32 s21, 0
	s_mov_b32 s99, 0
	s_mov_b64 s[38:39], -1
	s_mov_b64 s[40:41], 0
	v_mov_b32_e32 v1, v0
	v_mov_b32_e32 v2, v0
	v_mov_b32_e32 v3, v0
	v_mov_b32_e32 v4, v0
	v_mov_b32_e32 v5, v0
	v_mov_b32_e32 v6, v0
	v_mov_b32_e32 v7, v0
	v_mov_b32_e32 v8, v0
	v_mov_b32_e32 v9, v0
	v_mov_b32_e32 v10, v0
	v_mov_b32_e32 v11, v0
	v_mov_b32_e32 v12, v0
	v_mov_b32_e32 v13, v0
	v_mov_b32_e32 v14, v0
	v_mov_b32_e32 v15, v0
	v_mov_b32_e32 v16, v0
	v_mov_b32_e32 v17, v0
	v_mov_b32_e32 v18, v0
	v_mov_b32_e32 v19, v0
	v_mov_b32_e32 v20, v0
	v_mov_b32_e32 v21, v0
	v_mov_b32_e32 v22, v0
	v_mov_b32_e32 v23, v0
	v_mov_b32_e32 v24, v0
	v_mov_b32_e32 v25, v0
	v_mov_b32_e32 v26, v0
	v_mov_b32_e32 v27, v0
	v_mov_b32_e32 v28, v0
	v_mov_b32_e32 v29, v0
	v_mov_b32_e32 v30, v0
	v_mov_b32_e32 v31, v0
	v_mov_b32_e32 v32, v0
	v_mov_b32_e32 v33, v0
	v_mov_b32_e32 v34, v0
	v_mov_b32_e32 v35, v0
	v_mov_b32_e32 v36, v0
	v_mov_b32_e32 v37, v0
	v_mov_b32_e32 v38, v0
	v_mov_b32_e32 v39, v0
	v_mov_b32_e32 v40, v0
	v_mov_b32_e32 v41, v0
	v_mov_b32_e32 v42, v0
	v_mov_b32_e32 v43, v0
	v_mov_b32_e32 v44, v0
	v_mov_b32_e32 v45, v0
	v_mov_b32_e32 v46, v0
	v_mov_b32_e32 v47, v0
	v_mov_b32_e32 v48, v0
	v_mov_b32_e32 v49, v0
	v_mov_b32_e32 v50, v0
	v_mov_b32_e32 v51, v0
	v_mov_b32_e32 v52, v0
	v_mov_b32_e32 v53, v0
	v_mov_b32_e32 v54, v0
	v_mov_b32_e32 v55, v0
	v_mov_b32_e32 v56, v0
	v_mov_b32_e32 v57, v0
	v_mov_b32_e32 v58, v0
	v_mov_b32_e32 v59, v0
	v_mov_b32_e32 v60, v0
	v_mov_b32_e32 v61, v0
	v_mov_b32_e32 v62, v0
	v_mov_b32_e32 v63, v0
	v_mov_b32_e32 v64, v0
	v_mov_b32_e32 v65, v0
	v_mov_b32_e32 v66, v0
	v_mov_b32_e32 v67, v0
	v_mov_b32_e32 v68, v0
	v_mov_b32_e32 v69, v0
	v_mov_b32_e32 v70, v0
	v_mov_b32_e32 v71, v0
	v_mov_b32_e32 v72, v0
	v_mov_b32_e32 v73, v0
	v_mov_b32_e32 v74, v0
	v_mov_b32_e32 v75, v0
	v_mov_b32_e32 v76, v0
	v_mov_b32_e32 v77, v0
	v_mov_b32_e32 v78, v0
	v_mov_b32_e32 v79, v0
	v_mov_b32_e32 v80, v0
	v_mov_b32_e32 v81, v0
	v_mov_b32_e32 v82, v0
	v_mov_b32_e32 v83, v0
	v_mov_b32_e32 v84, v0
	v_mov_b32_e32 v85, v0
	v_mov_b32_e32 v86, v0
	v_mov_b32_e32 v87, v0
	v_mov_b32_e32 v88, v0
	v_mov_b32_e32 v89, v0
	v_mov_b32_e32 v90, v0
	v_mov_b32_e32 v91, v0
	v_mov_b32_e32 v92, v0
	v_mov_b32_e32 v93, v0
	v_mov_b32_e32 v94, v0
	v_mov_b32_e32 v95, v0
	v_mov_b32_e32 v96, v0
	v_mov_b32_e32 v97, v0
	v_mov_b32_e32 v98, v0
	v_mov_b32_e32 v99, v0
	v_mov_b32_e32 v100, v0
	v_mov_b32_e32 v101, v0
	v_mov_b32_e32 v102, v0
	v_mov_b32_e32 v103, v0
	v_mov_b32_e32 v104, v0
	v_mov_b32_e32 v105, v0
	v_mov_b32_e32 v106, v0
	v_mov_b32_e32 v107, v0
	v_mov_b32_e32 v108, v0
	v_mov_b32_e32 v109, v0
	v_mov_b32_e32 v110, v0
	v_mov_b32_e32 v111, v0
	v_mov_b32_e32 v112, v0
	v_mov_b32_e32 v113, v0
	v_mov_b32_e32 v114, v0
	v_mov_b32_e32 v115, v0
	v_mov_b32_e32 v116, v0
	v_mov_b32_e32 v117, v0
	v_mov_b32_e32 v118, v0
	v_mov_b32_e32 v119, v0
	v_mov_b32_e32 v120, v0
	v_mov_b32_e32 v121, v0
	v_mov_b32_e32 v122, v0
	v_mov_b32_e32 v123, v0
	v_mov_b32_e32 v124, v0
	v_mov_b32_e32 v125, v0
	v_mov_b32_e32 v126, v0
	v_mov_b32_e32 v127, v0
.LBB0_1082:
	s_add_u32 s23, s30, s21
	s_addc_u32 s25, s31, 0
	s_add_u32 s37, s23, 0x100
	s_addc_u32 s44, s25, 0
	s_and_b64 s[42:43], s[40:41], exec
	s_cselect_b32 s45, s29, s44
	s_cselect_b32 s44, s28, s37
	s_add_u32 s21, s26, s21
	s_addc_u32 s37, s27, 0
	s_add_u32 s21, s21, 0x100
	s_addc_u32 s37, s37, 0
	s_and_b64 s[40:41], s[40:41], exec
	s_cselect_b32 s47, s35, s37
	s_cselect_b32 s46, s34, s21
	s_add_u32 s50, s23, 0x80080
	s_addc_u32 s51, s25, 0
	s_add_i32 s76, s62, s2
	ds_read_b128 v[146:149], v131
	ds_read_b128 v[150:153], v131 offset:1024
	ds_read_b128 v[154:157], v131 offset:2048
	ds_read_b128 v[158:161], v131 offset:3072
	ds_read_b128 v[166:169], v132
	ds_read_b128 v[170:173], v132 offset:1024
	ds_read_b128 v[174:177], v132 offset:2048
	ds_read_b128 v[180:183], v132 offset:3072
	s_add_i32 m0, s3, 0xc000
	s_add_i32 s77, s3, 0xe000
	s_add_i32 s73, s76, 0x2000
	s_add_u32 s48, s46, 0x80000
	s_addc_u32 s49, s47, 0
	s_add_i32 s75, s63, s2
	s_add_i32 s74, s75, 0x2000
	s_add_i32 s72, 0, 0x18000
	s_add_i32 s71, 0, 0x1c000
	s_add_u32 s42, s44, 0x80000
	s_addc_u32 s43, s45, 0
	s_add_i32 s37, s72, s2
	s_add_i32 s23, s37, 0x2000
	s_add_u32 s40, s46, 0x80080
	s_addc_u32 s41, s47, 0
	s_add_i32 s25, s71, s2
	s_add_i32 s21, s25, 0x2000
	v_lshl_add_u64 v[134:135], s[50:51], 0, v[138:139]
	ds_read_b128 v[184:187], v133
	ds_read_b128 v[188:191], v133 offset:1024
	ds_read_b128 v[192:195], v133 offset:2048
	ds_read_b128 v[196:199], v133 offset:3072
	ds_read_b128 v[200:203], v133 offset:4096
	ds_read_b128 v[204:207], v133 offset:5120
	ds_read_b128 v[210:213], v133 offset:6144
	ds_read_b128 v[214:217], v133 offset:7168
	global_load_lds_dwordx4 v[134:135], off
	v_lshl_add_u64 v[134:135], s[50:51], 0, v[142:143]
	s_mov_b32 m0, s77
	s_nop 0
	global_load_lds_dwordx4 v[134:135], off
	s_waitcnt vmcnt(8)
	s_waitcnt lgkmcnt(0)
	s_barrier
	s_setprio 1
	s_waitcnt lgkmcnt(0)
	v_mfma_f32_16x16x32_bf16 v[124:127], v[146:149], v[184:187], v[124:127]
	v_mfma_f32_16x16x32_bf16 v[120:123], v[154:157], v[184:187], v[120:123]
	v_mfma_f32_16x16x32_bf16 v[116:119], v[146:149], v[192:195], v[116:119]
	v_mfma_f32_16x16x32_bf16 v[112:115], v[154:157], v[192:195], v[112:115]
	v_mfma_f32_16x16x32_bf16 v[108:111], v[146:149], v[200:203], v[108:111]
	v_mfma_f32_16x16x32_bf16 v[104:107], v[154:157], v[200:203], v[104:107]
	v_mfma_f32_16x16x32_bf16 v[100:103], v[146:149], v[210:213], v[100:103]
	v_mfma_f32_16x16x32_bf16 v[96:99], v[154:157], v[210:213], v[96:99]
	v_mfma_f32_16x16x32_bf16 v[124:127], v[150:153], v[188:191], v[124:127]
	v_mfma_f32_16x16x32_bf16 v[120:123], v[158:161], v[188:191], v[120:123]
	v_mfma_f32_16x16x32_bf16 v[116:119], v[150:153], v[196:199], v[116:119]
	v_mfma_f32_16x16x32_bf16 v[112:115], v[158:161], v[196:199], v[112:115]
	v_mfma_f32_16x16x32_bf16 v[108:111], v[150:153], v[204:207], v[108:111]
	v_mfma_f32_16x16x32_bf16 v[104:107], v[158:161], v[204:207], v[104:107]
	v_mfma_f32_16x16x32_bf16 v[100:103], v[150:153], v[214:217], v[100:103]
	v_mfma_f32_16x16x32_bf16 v[96:99], v[158:161], v[214:217], v[96:99]
	v_mfma_f32_16x16x32_bf16 v[92:95], v[166:169], v[184:187], v[92:95]
	v_mfma_f32_16x16x32_bf16 v[88:91], v[174:177], v[184:187], v[88:91]
	v_mfma_f32_16x16x32_bf16 v[84:87], v[166:169], v[192:195], v[84:87]
	v_mfma_f32_16x16x32_bf16 v[80:83], v[174:177], v[192:195], v[80:83]
	v_mfma_f32_16x16x32_bf16 v[76:79], v[166:169], v[200:203], v[76:79]
	v_mfma_f32_16x16x32_bf16 v[72:75], v[174:177], v[200:203], v[72:75]
	v_mfma_f32_16x16x32_bf16 v[68:71], v[166:169], v[210:213], v[68:71]
	v_mfma_f32_16x16x32_bf16 v[64:67], v[174:177], v[210:213], v[64:67]
	v_mfma_f32_16x16x32_bf16 v[92:95], v[170:173], v[188:191], v[92:95]
	v_mfma_f32_16x16x32_bf16 v[88:91], v[180:183], v[188:191], v[88:91]
	v_mfma_f32_16x16x32_bf16 v[84:87], v[170:173], v[196:199], v[84:87]
	v_mfma_f32_16x16x32_bf16 v[80:83], v[180:183], v[196:199], v[80:83]
	v_mfma_f32_16x16x32_bf16 v[76:79], v[170:173], v[204:207], v[76:79]
	v_mfma_f32_16x16x32_bf16 v[72:75], v[180:183], v[204:207], v[72:75]
	v_mfma_f32_16x16x32_bf16 v[68:71], v[170:173], v[214:217], v[68:71]
	v_mfma_f32_16x16x32_bf16 v[64:67], v[180:183], v[214:217], v[64:67]
	s_setprio 0
	s_barrier
	s_mov_b32 m0, s76
	v_lshl_add_u64 v[134:135], s[46:47], 0, v[140:141]
	ds_read_b128 v[184:187], v133 offset:16384
	ds_read_b128 v[188:191], v133 offset:17408
	ds_read_b128 v[192:195], v133 offset:18432
	ds_read_b128 v[196:199], v133 offset:19456
	ds_read_b128 v[200:203], v133 offset:20480
	ds_read_b128 v[204:207], v133 offset:21504
	ds_read_b128 v[210:213], v133 offset:22528
	ds_read_b128 v[214:217], v133 offset:23552
	global_load_lds_dwordx4 v[134:135], off
	v_lshl_add_u64 v[162:163], s[46:47], 0, v[144:145]
	s_mov_b32 m0, s73
	v_lshl_add_u64 v[218:219], s[48:49], 0, v[140:141]
	global_load_lds_dwordx4 v[162:163], off
	s_mov_b32 m0, s75
	v_lshl_add_u64 v[220:221], s[44:45], 0, v[142:143]
	global_load_lds_dwordx4 v[218:219], off
	v_lshl_add_u64 v[218:219], s[48:49], 0, v[144:145]
	s_mov_b32 m0, s74
	s_nop 0
	global_load_lds_dwordx4 v[218:219], off
	v_lshl_add_u64 v[218:219], s[44:45], 0, v[138:139]
	s_mov_b32 m0, s3
	s_nop 0
	global_load_lds_dwordx4 v[218:219], off
	s_mov_b32 m0, s56
	s_nop 0
	global_load_lds_dwordx4 v[220:221], off
	s_waitcnt vmcnt(8)
	s_waitcnt lgkmcnt(0)
	s_barrier
	s_setprio 1
	s_waitcnt lgkmcnt(0)
	v_mfma_f32_16x16x32_bf16 v[60:63], v[146:149], v[184:187], v[60:63]
	v_mfma_f32_16x16x32_bf16 v[56:59], v[154:157], v[184:187], v[56:59]
	v_mfma_f32_16x16x32_bf16 v[52:55], v[146:149], v[192:195], v[52:55]
	v_mfma_f32_16x16x32_bf16 v[48:51], v[154:157], v[192:195], v[48:51]
	v_mfma_f32_16x16x32_bf16 v[44:47], v[146:149], v[200:203], v[44:47]
	v_mfma_f32_16x16x32_bf16 v[40:43], v[154:157], v[200:203], v[40:43]
	v_mfma_f32_16x16x32_bf16 v[36:39], v[146:149], v[210:213], v[36:39]
	v_mfma_f32_16x16x32_bf16 v[32:35], v[154:157], v[210:213], v[32:35]
	v_mfma_f32_16x16x32_bf16 v[60:63], v[150:153], v[188:191], v[60:63]
	v_mfma_f32_16x16x32_bf16 v[56:59], v[158:161], v[188:191], v[56:59]
	v_mfma_f32_16x16x32_bf16 v[52:55], v[150:153], v[196:199], v[52:55]
	v_mfma_f32_16x16x32_bf16 v[48:51], v[158:161], v[196:199], v[48:51]
	v_mfma_f32_16x16x32_bf16 v[44:47], v[150:153], v[204:207], v[44:47]
	v_mfma_f32_16x16x32_bf16 v[40:43], v[158:161], v[204:207], v[40:43]
	v_mfma_f32_16x16x32_bf16 v[36:39], v[150:153], v[214:217], v[36:39]
	v_mfma_f32_16x16x32_bf16 v[32:35], v[158:161], v[214:217], v[32:35]
	v_mfma_f32_16x16x32_bf16 v[28:31], v[166:169], v[184:187], v[28:31]
	v_mfma_f32_16x16x32_bf16 v[24:27], v[174:177], v[184:187], v[24:27]
	v_mfma_f32_16x16x32_bf16 v[20:23], v[166:169], v[192:195], v[20:23]
	v_mfma_f32_16x16x32_bf16 v[16:19], v[174:177], v[192:195], v[16:19]
	v_mfma_f32_16x16x32_bf16 v[12:15], v[166:169], v[200:203], v[12:15]
	v_mfma_f32_16x16x32_bf16 v[8:11], v[174:177], v[200:203], v[8:11]
	v_mfma_f32_16x16x32_bf16 v[4:7], v[166:169], v[210:213], v[4:7]
	v_mfma_f32_16x16x32_bf16 v[0:3], v[174:177], v[210:213], v[0:3]
	v_mfma_f32_16x16x32_bf16 v[28:31], v[170:173], v[188:191], v[28:31]
	v_mfma_f32_16x16x32_bf16 v[24:27], v[180:183], v[188:191], v[24:27]
	v_mfma_f32_16x16x32_bf16 v[20:23], v[170:173], v[196:199], v[20:23]
	v_mfma_f32_16x16x32_bf16 v[16:19], v[180:183], v[196:199], v[16:19]
	v_mfma_f32_16x16x32_bf16 v[12:15], v[170:173], v[204:207], v[12:15]
	v_mfma_f32_16x16x32_bf16 v[8:11], v[180:183], v[204:207], v[8:11]
	v_mfma_f32_16x16x32_bf16 v[4:7], v[170:173], v[214:217], v[4:7]
	v_mfma_f32_16x16x32_bf16 v[0:3], v[180:183], v[214:217], v[0:3]
	s_setprio 0
	s_barrier
	v_add_u32_e32 v137, s72, v130
	ds_read_b128 v[146:149], v137
	ds_read_b128 v[150:153], v137 offset:1024
	ds_read_b128 v[154:157], v137 offset:2048
	ds_read_b128 v[158:161], v137 offset:3072
	v_add_u32_e32 v137, s71, v130
	ds_read_b128 v[166:169], v137
	ds_read_b128 v[170:173], v137 offset:1024
	ds_read_b128 v[174:177], v137 offset:2048
	ds_read_b128 v[180:183], v137 offset:3072
	s_mov_b32 m0, s57
	v_lshl_add_u64 v[222:223], s[42:43], 0, v[138:139]
	ds_read_b128 v[184:187], v133 offset:32768
	ds_read_b128 v[188:191], v133 offset:33792
	ds_read_b128 v[192:195], v133 offset:34816
	ds_read_b128 v[196:199], v133 offset:35840
	ds_read_b128 v[200:203], v133 offset:36864
	ds_read_b128 v[204:207], v133 offset:37888
	ds_read_b128 v[210:213], v133 offset:38912
	ds_read_b128 v[214:217], v133 offset:39936
	global_load_lds_dwordx4 v[222:223], off
	v_lshl_add_u64 v[222:223], s[42:43], 0, v[142:143]
	s_mov_b32 m0, s58
	s_nop 0
	global_load_lds_dwordx4 v[222:223], off
	s_waitcnt vmcnt(8)
	s_waitcnt lgkmcnt(0)
	s_barrier
	s_setprio 1
	s_waitcnt lgkmcnt(0)
	v_mfma_f32_16x16x32_bf16 v[124:127], v[146:149], v[184:187], v[124:127]
	v_mfma_f32_16x16x32_bf16 v[120:123], v[154:157], v[184:187], v[120:123]
	v_mfma_f32_16x16x32_bf16 v[116:119], v[146:149], v[192:195], v[116:119]
	v_mfma_f32_16x16x32_bf16 v[112:115], v[154:157], v[192:195], v[112:115]
	v_mfma_f32_16x16x32_bf16 v[108:111], v[146:149], v[200:203], v[108:111]
	v_mfma_f32_16x16x32_bf16 v[104:107], v[154:157], v[200:203], v[104:107]
	v_mfma_f32_16x16x32_bf16 v[100:103], v[146:149], v[210:213], v[100:103]
	v_mfma_f32_16x16x32_bf16 v[96:99], v[154:157], v[210:213], v[96:99]
	v_mfma_f32_16x16x32_bf16 v[124:127], v[150:153], v[188:191], v[124:127]
	v_mfma_f32_16x16x32_bf16 v[120:123], v[158:161], v[188:191], v[120:123]
	v_mfma_f32_16x16x32_bf16 v[116:119], v[150:153], v[196:199], v[116:119]
	v_mfma_f32_16x16x32_bf16 v[112:115], v[158:161], v[196:199], v[112:115]
	v_mfma_f32_16x16x32_bf16 v[108:111], v[150:153], v[204:207], v[108:111]
	v_mfma_f32_16x16x32_bf16 v[104:107], v[158:161], v[204:207], v[104:107]
	v_mfma_f32_16x16x32_bf16 v[100:103], v[150:153], v[214:217], v[100:103]
	v_mfma_f32_16x16x32_bf16 v[96:99], v[158:161], v[214:217], v[96:99]
	v_mfma_f32_16x16x32_bf16 v[92:95], v[166:169], v[184:187], v[92:95]
	v_mfma_f32_16x16x32_bf16 v[88:91], v[174:177], v[184:187], v[88:91]
	v_mfma_f32_16x16x32_bf16 v[84:87], v[166:169], v[192:195], v[84:87]
	v_mfma_f32_16x16x32_bf16 v[80:83], v[174:177], v[192:195], v[80:83]
	v_mfma_f32_16x16x32_bf16 v[76:79], v[166:169], v[200:203], v[76:79]
	v_mfma_f32_16x16x32_bf16 v[72:75], v[174:177], v[200:203], v[72:75]
	v_mfma_f32_16x16x32_bf16 v[68:71], v[166:169], v[210:213], v[68:71]
	v_mfma_f32_16x16x32_bf16 v[64:67], v[174:177], v[210:213], v[64:67]
	v_mfma_f32_16x16x32_bf16 v[92:95], v[170:173], v[188:191], v[92:95]
	v_mfma_f32_16x16x32_bf16 v[88:91], v[180:183], v[188:191], v[88:91]
	v_mfma_f32_16x16x32_bf16 v[84:87], v[170:173], v[196:199], v[84:87]
	v_mfma_f32_16x16x32_bf16 v[80:83], v[180:183], v[196:199], v[80:83]
	v_mfma_f32_16x16x32_bf16 v[76:79], v[170:173], v[204:207], v[76:79]
	v_mfma_f32_16x16x32_bf16 v[72:75], v[180:183], v[204:207], v[72:75]
	v_mfma_f32_16x16x32_bf16 v[68:71], v[170:173], v[214:217], v[68:71]
	v_mfma_f32_16x16x32_bf16 v[64:67], v[180:183], v[214:217], v[64:67]
	s_setprio 0
	s_barrier
	s_mov_b32 m0, s37
	v_lshl_add_u64 v[134:135], v[134:135], 0, s[16:17]
	ds_read_b128 v[184:187], v133 offset:49152
	ds_read_b128 v[188:191], v133 offset:50176
	ds_read_b128 v[192:195], v133 offset:51200
	ds_read_b128 v[196:199], v133 offset:52224
	ds_read_b128 v[200:203], v133 offset:53248
	ds_read_b128 v[204:207], v133 offset:54272
	ds_read_b128 v[210:213], v133 offset:55296
	ds_read_b128 v[214:217], v133 offset:56320
	global_load_lds_dwordx4 v[134:135], off
	v_lshl_add_u64 v[134:135], v[162:163], 0, s[16:17]
	s_mov_b32 m0, s23
	s_nop 0
	global_load_lds_dwordx4 v[134:135], off
	v_lshl_add_u64 v[134:135], s[40:41], 0, v[140:141]
	s_mov_b32 m0, s25
	s_nop 0
	global_load_lds_dwordx4 v[134:135], off
	v_lshl_add_u64 v[134:135], s[40:41], 0, v[144:145]
	s_mov_b32 m0, s21
	s_nop 0
	global_load_lds_dwordx4 v[134:135], off
	v_lshl_add_u64 v[134:135], v[218:219], 0, s[16:17]
	s_mov_b32 m0, s60
	s_nop 0
	global_load_lds_dwordx4 v[134:135], off
	v_lshl_add_u64 v[134:135], v[220:221], 0, s[16:17]
	s_mov_b32 m0, s61
	s_nop 0
	global_load_lds_dwordx4 v[134:135], off
	s_waitcnt vmcnt(8)
	s_waitcnt lgkmcnt(0)
	s_barrier
	s_setprio 1
	s_waitcnt lgkmcnt(0)
	v_mfma_f32_16x16x32_bf16 v[60:63], v[146:149], v[184:187], v[60:63]
	v_mfma_f32_16x16x32_bf16 v[56:59], v[154:157], v[184:187], v[56:59]
	v_mfma_f32_16x16x32_bf16 v[52:55], v[146:149], v[192:195], v[52:55]
	v_mfma_f32_16x16x32_bf16 v[48:51], v[154:157], v[192:195], v[48:51]
	v_mfma_f32_16x16x32_bf16 v[44:47], v[146:149], v[200:203], v[44:47]
	v_mfma_f32_16x16x32_bf16 v[40:43], v[154:157], v[200:203], v[40:43]
	v_mfma_f32_16x16x32_bf16 v[36:39], v[146:149], v[210:213], v[36:39]
	v_mfma_f32_16x16x32_bf16 v[32:35], v[154:157], v[210:213], v[32:35]
	v_mfma_f32_16x16x32_bf16 v[60:63], v[150:153], v[188:191], v[60:63]
	v_mfma_f32_16x16x32_bf16 v[56:59], v[158:161], v[188:191], v[56:59]
	v_mfma_f32_16x16x32_bf16 v[52:55], v[150:153], v[196:199], v[52:55]
	v_mfma_f32_16x16x32_bf16 v[48:51], v[158:161], v[196:199], v[48:51]
	v_mfma_f32_16x16x32_bf16 v[44:47], v[150:153], v[204:207], v[44:47]
	v_mfma_f32_16x16x32_bf16 v[40:43], v[158:161], v[204:207], v[40:43]
	v_mfma_f32_16x16x32_bf16 v[36:39], v[150:153], v[214:217], v[36:39]
	v_mfma_f32_16x16x32_bf16 v[32:35], v[158:161], v[214:217], v[32:35]
	v_mfma_f32_16x16x32_bf16 v[28:31], v[166:169], v[184:187], v[28:31]
	v_mfma_f32_16x16x32_bf16 v[24:27], v[174:177], v[184:187], v[24:27]
	v_mfma_f32_16x16x32_bf16 v[20:23], v[166:169], v[192:195], v[20:23]
	v_mfma_f32_16x16x32_bf16 v[16:19], v[174:177], v[192:195], v[16:19]
	v_mfma_f32_16x16x32_bf16 v[12:15], v[166:169], v[200:203], v[12:15]
	v_mfma_f32_16x16x32_bf16 v[8:11], v[174:177], v[200:203], v[8:11]
	v_mfma_f32_16x16x32_bf16 v[4:7], v[166:169], v[210:213], v[4:7]
	v_mfma_f32_16x16x32_bf16 v[0:3], v[174:177], v[210:213], v[0:3]
	v_mfma_f32_16x16x32_bf16 v[28:31], v[170:173], v[188:191], v[28:31]
	v_mfma_f32_16x16x32_bf16 v[24:27], v[180:183], v[188:191], v[24:27]
	v_mfma_f32_16x16x32_bf16 v[20:23], v[170:173], v[196:199], v[20:23]
	v_mfma_f32_16x16x32_bf16 v[16:19], v[180:183], v[196:199], v[16:19]
	v_mfma_f32_16x16x32_bf16 v[12:15], v[170:173], v[204:207], v[12:15]
	v_mfma_f32_16x16x32_bf16 v[8:11], v[180:183], v[204:207], v[8:11]
	v_mfma_f32_16x16x32_bf16 v[4:7], v[170:173], v[214:217], v[4:7]
	v_mfma_f32_16x16x32_bf16 v[0:3], v[180:183], v[214:217], v[0:3]
	s_setprio 0
	s_barrier
	s_add_i32 s99, s99, 0x100
	s_mov_b32 s21, s99
	s_cmp_eq_u32 s99, 0x300
	s_cselect_b64 s[40:41], -1, 0
	s_cmp_lg_u32 s99, 0x400
	s_cbranch_scc1 .LBB0_1082
	s_and_b64 vcc, exec, s[18:19]
	s_cbranch_vccz .LBB0_1085
	s_barrier

.LBB0_1144:
	s_ashr_i32 s50, s48, 3
	s_add_i32 s0, s50, s6
	s_ashr_i32 s10, s0, 31
	s_lshr_b32 s10, s10, 29
	s_add_i32 s10, s0, s10
	s_ashr_i32 s11, s10, 3
	s_and_b32 s10, s10, -8
	s_sub_i32 s0, s0, s10
	s_cmp_lt_i32 s0, 0
	s_cselect_b32 s10, 36, 35
	s_mul_i32 s0, s0, s10
	s_add_i32 s0, s0, s11
	s_ashr_i32 s10, s0, 31
	s_lshr_b32 s10, s10, 27
	s_add_i32 s12, s0, s10
	s_ashr_i32 s10, s12, 5
	s_lshl_b32 s10, s10, 2
	s_sub_i32 s11, 35, s10
	s_min_i32 s11, s11, 4
	s_abs_i32 s49, s11
	v_cvt_f32_u32_e32 v0, s49
	s_sub_i32 s51, 0, s49
	s_andn2_b32 s12, s12, 31
	s_sub_i32 s12, s0, s12
	v_rcp_iflag_f32_e32 v0, v0
	s_abs_i32 s0, s12
	s_xor_b32 s13, s12, s11
	s_ashr_i32 s13, s13, 31
	v_mul_f32_e32 v0, 0x4f7ffffe, v0
	v_cvt_u32_f32_e32 v0, v0
	s_nop 0
	v_readfirstlane_b32 s52, v0
	s_mul_i32 s51, s51, s52
	s_mul_hi_u32 s51, s52, s51
	s_add_i32 s52, s52, s51
	s_mul_hi_u32 s51, s0, s52
	s_mul_i32 s52, s51, s49
	s_sub_i32 s0, s0, s52
	s_add_i32 s53, s51, 1
	s_sub_i32 s52, s0, s49
	s_cmp_ge_u32 s0, s49
	s_cselect_b32 s51, s53, s51
	s_cselect_b32 s0, s52, s0
	s_add_i32 s52, s51, 1
	s_cmp_ge_u32 s0, s49
	s_cselect_b32 s49, s52, s51
	s_ashr_i32 s51, s50, 31
	s_lshl_b64 s[50:51], s[50:51], 20
	v_lshl_add_u64 v[0:1], v[128:129], 0, s[50:51]
	s_bfe_u32 s50, s48, 0x10002
	s_and_b32 s51, s48, 3
	s_lshl_b32 s0, s50, 17
	s_lshl_b32 s52, s51, 14
	s_or_b32 s0, s0, s52
	v_lshl_add_u64 v[56:57], v[0:1], 0, s[0:1]
	v_add_co_u32_e32 v0, vcc, s3, v56
	s_xor_b32 s0, s49, s13
	s_nop 0
	v_addc_co_u32_e32 v1, vcc, 0, v57, vcc
	global_load_dwordx4 v[64:67], v[56:57], off
	global_load_dwordx4 v[68:71], v[0:1], off
	v_add_co_u32_e32 v0, vcc, s14, v56
	s_sub_i32 s0, s0, s13
	s_nop 0
	v_addc_co_u32_e32 v1, vcc, 0, v57, vcc
	v_add_co_u32_e32 v2, vcc, s15, v56
	s_mul_i32 s11, s0, s11
	s_nop 0
	v_addc_co_u32_e32 v3, vcc, 0, v57, vcc
	global_load_dwordx4 v[76:79], v[0:1], off
	global_load_dwordx4 v[72:75], v[2:3], off
	v_add_co_u32_e32 v0, vcc, s16, v56
	s_sub_i32 s11, s12, s11
	s_nop 0
	v_addc_co_u32_e32 v1, vcc, 0, v57, vcc
	v_add_co_u32_e32 v2, vcc, s17, v56
	s_or_b32 s12, s51, s2
	s_nop 0
	v_addc_co_u32_e32 v3, vcc, 0, v57, vcc
	v_add_co_u32_e32 v0, vcc, s18, v56
	s_add_i32 s10, s10, s11
	s_nop 0
	v_addc_co_u32_e32 v1, vcc, 0, v57, vcc
	v_add_co_u32_e32 v2, vcc, s19, v56
	s_lshl_b32 s11, s50, 7
	s_nop 0
	v_addc_co_u32_e32 v3, vcc, 0, v57, vcc
	v_add_co_u32_e32 v0, vcc, s20, v56
	s_lshl_b32 s12, s12, 4
	s_nop 0
	v_addc_co_u32_e32 v1, vcc, 0, v57, vcc
	v_add_co_u32_e32 v2, vcc, s21, v56
	s_lshl_b32 s10, s10, 8
	s_nop 0
	v_addc_co_u32_e32 v3, vcc, 0, v57, vcc
	global_load_dwordx4 v[88:91], v[0:1], off
	global_load_dwordx4 v[100:103], v[2:3], off
	v_add_co_u32_e32 v0, vcc, s22, v56
	s_add_i32 s12, s12, s11
	s_nop 0
	v_addc_co_u32_e32 v1, vcc, 0, v57, vcc
	v_add_co_u32_e32 v2, vcc, s23, v56
	s_add_i32 s12, s12, s10
	s_nop 0
	v_addc_co_u32_e32 v3, vcc, 0, v57, vcc
	global_load_dwordx4 v[108:111], v[0:1], off
	global_load_dwordx4 v[104:107], v[2:3], off
	v_add_co_u32_e32 v0, vcc, s24, v56
	v_or_b32_e32 v130, s12, v164
	s_nop 0
	v_addc_co_u32_e32 v1, vcc, 0, v57, vcc
	v_add_co_u32_e32 v2, vcc, s25, v56
	s_nop 1
	v_addc_co_u32_e32 v3, vcc, 0, v57, vcc
	v_add_co_u32_e32 v0, vcc, s26, v56
	s_nop 1
	v_addc_co_u32_e32 v1, vcc, 0, v57, vcc
	v_add_co_u32_e32 v2, vcc, s27, v56
	s_nop 1
	v_addc_co_u32_e32 v3, vcc, 0, v57, vcc
	v_add_co_u32_e32 v0, vcc, s28, v56
	s_nop 1
	v_addc_co_u32_e32 v1, vcc, 0, v57, vcc
	v_add_co_u32_e32 v4, vcc, s29, v56
	s_nop 1
	v_addc_co_u32_e32 v5, vcc, 0, v57, vcc
	v_add_co_u32_e32 v8, vcc, s30, v56
	global_load_dwordx4 v[0:3], v[0:1], off
	s_nop 0
	global_load_dwordx4 v[4:7], v[4:5], off
	v_addc_co_u32_e32 v9, vcc, 0, v57, vcc
	v_add_co_u32_e32 v10, vcc, s31, v56
	s_nop 1
	v_addc_co_u32_e32 v11, vcc, 0, v57, vcc
	v_add_co_u32_e32 v16, vcc, s34, v56
	global_load_dwordx4 v[12:15], v[8:9], off
	s_nop 0
	global_load_dwordx4 v[8:11], v[10:11], off
	v_addc_co_u32_e32 v17, vcc, 0, v57, vcc
	v_add_co_u32_e32 v18, vcc, s35, v56
	s_nop 1
	v_addc_co_u32_e32 v19, vcc, 0, v57, vcc
	v_add_co_u32_e32 v24, vcc, s36, v56
	s_nop 0
	s_nop 0
	v_addc_co_u32_e32 v25, vcc, 0, v57, vcc
	v_add_co_u32_e32 v26, vcc, s37, v56
	s_nop 1
	v_addc_co_u32_e32 v27, vcc, 0, v57, vcc
	v_add_co_u32_e32 v24, vcc, s38, v56
	s_nop 1
	v_addc_co_u32_e32 v25, vcc, 0, v57, vcc
	v_add_co_u32_e32 v36, vcc, s39, v56
	s_nop 1
	v_addc_co_u32_e32 v37, vcc, 0, v57, vcc
	v_add_co_u32_e32 v40, vcc, s40, v56
	global_load_dwordx4 v[24:27], v[24:25], off
	s_nop 0
	global_load_dwordx4 v[36:39], v[36:37], off
	v_addc_co_u32_e32 v41, vcc, 0, v57, vcc
	v_add_co_u32_e32 v42, vcc, s41, v56
	s_nop 1
	v_addc_co_u32_e32 v43, vcc, 0, v57, vcc
	v_add_co_u32_e32 v48, vcc, s42, v56
	global_load_dwordx4 v[44:47], v[40:41], off
	s_nop 0
	global_load_dwordx4 v[40:43], v[42:43], off
	v_addc_co_u32_e32 v49, vcc, 0, v57, vcc
	v_add_co_u32_e32 v50, vcc, s43, v56
	s_nop 1
	v_addc_co_u32_e32 v51, vcc, 0, v57, vcc
	v_add_co_u32_e32 v58, vcc, s44, v56
	s_nop 0
	s_nop 0
	v_addc_co_u32_e32 v59, vcc, 0, v57, vcc
	v_add_co_u32_e32 v56, vcc, 0x1d2000, v56
	s_nop 1
	v_addc_co_u32_e32 v57, vcc, 0, v57, vcc
	s_nop 0
	v_cmp_lt_i32_e32 vcc, s45, v130
	s_and_saveexec_b64 s[10:11], vcc
	s_xor_b64 s[10:11], exec, s[10:11]
	s_cbranch_execz .LBB0_1146
	v_add_u32_e32 v136, 0xffffdfc0, v130
	v_readlane_b32 s64, v245, 6
	s_cmpk_lt_u32 s12, 0x2240
	v_lshlrev_b64 v[132:133], 13, v[136:137]
	v_readlane_b32 s66, v245, 8
	v_readlane_b32 s67, v245, 9
	s_cselect_b64 vcc, -1, 0
	v_readlane_b32 s65, v245, 7
	v_lshl_add_u64 v[132:133], s[66:67], 0, v[132:133]
	v_readlane_b32 s68, v245, 10
	v_readlane_b32 s69, v245, 11
	v_readlane_b32 s70, v245, 12
	v_readlane_b32 s71, v245, 13
	v_readlane_b32 s72, v245, 14
	v_readlane_b32 s73, v245, 15
	v_readlane_b32 s74, v245, 16
	v_readlane_b32 s75, v245, 17
	v_readlane_b32 s76, v245, 18
	v_readlane_b32 s77, v245, 19
	v_readlane_b32 s78, v245, 20
	v_readlane_b32 s79, v245, 21
	v_cndmask_b32_e32 v133, 0, v133, vcc
	v_cndmask_b32_e32 v132, 0, v132, vcc

.LBB0_1152:
	s_or_b64 exec, exec, s[10:11]
	s_waitcnt vmcnt(14)
	v_pk_add_f32 v[66:67], v[66:67], v[70:71]
	v_pk_add_f32 v[64:65], v[64:65], v[68:69]
	s_waitcnt vmcnt(10)
	v_pk_add_f32 v[68:69], v[90:91], v[102:103]
	v_pk_add_f32 v[70:71], v[88:89], v[100:101]
	v_pk_add_f32 v[66:67], v[66:67], v[78:79]
	v_pk_add_f32 v[64:65], v[64:65], v[76:77]
	s_waitcnt vmcnt(9)
	v_pk_add_f32 v[68:69], v[68:69], v[110:111]
	v_pk_add_f32 v[70:71], v[70:71], v[108:109]
	v_pk_add_f32 v[66:67], v[66:67], v[74:75]
	v_pk_add_f32 v[64:65], v[64:65], v[72:73]
	s_waitcnt vmcnt(8)
	v_pk_add_f32 v[68:69], v[68:69], v[106:107]
	v_pk_add_f32 v[70:71], v[70:71], v[104:105]
	s_waitcnt vmcnt(8)
	s_waitcnt vmcnt(8)
	v_lshl_or_b32 v74, s0, 8, v140
	s_waitcnt vmcnt(8)
	v_mov_b32_e32 v72, v70
	v_mov_b32_e32 v73, v71
	v_ashrrev_i32_e32 v75, 31, v74
	s_waitcnt vmcnt(8)
	v_mov_b32_e32 v70, v68
	v_mov_b32_e32 v71, v69
	v_mov_b32_e32 v68, v72
	v_mov_b32_e32 v69, v73
	v_cmp_ne_u64_e32 vcc, 0, v[132:133]
	v_lshl_add_u64 v[72:73], v[74:75], 2, v[132:133]
	s_and_saveexec_b64 s[10:11], vcc
	s_cbranch_execz .LBB0_1154
	global_load_dwordx4 v[76:79], v[72:73], off nt
	global_load_dwordx4 v[80:83], v[72:73], off offset:16 nt
	s_waitcnt vmcnt(1)
	v_pk_add_f32 v[66:67], v[66:67], v[78:79]
	v_pk_add_f32 v[64:65], v[64:65], v[76:77]
	s_waitcnt vmcnt(0)
	v_pk_add_f32 v[70:71], v[70:71], v[82:83]
	v_pk_add_f32 v[68:69], v[68:69], v[80:81]
.LBB0_1154:
	s_or_b64 exec, exec, s[10:11]
	s_waitcnt vmcnt(6)
	v_pk_add_f32 v[2:3], v[2:3], v[6:7]
	v_pk_add_f32 v[0:1], v[0:1], v[4:5]
	s_waitcnt vmcnt(2)
	v_pk_add_f32 v[4:5], v[26:27], v[38:39]
	v_pk_add_f32 v[6:7], v[24:25], v[36:37]
	s_waitcnt vmcnt(1)
	v_pk_add_f32 v[4:5], v[4:5], v[46:47]
	v_pk_add_f32 v[6:7], v[6:7], v[44:45]
	v_pk_add_f32 v[2:3], v[2:3], v[14:15]
	v_pk_add_f32 v[0:1], v[0:1], v[12:13]
	s_waitcnt vmcnt(0)
	v_pk_add_f32 v[4:5], v[4:5], v[42:43]
	v_pk_add_f32 v[6:7], v[6:7], v[40:41]
	v_pk_add_f32 v[2:3], v[2:3], v[10:11]
	v_pk_add_f32 v[0:1], v[0:1], v[8:9]
	s_waitcnt vmcnt(0)
	v_ashrrev_i32_e32 v131, 31, v130
	s_waitcnt vmcnt(0)
	v_lshlrev_b64 v[76:77], 13, v[130:131]
	s_waitcnt vmcnt(0)
	v_mov_b32_e32 v8, v6
	v_mov_b32_e32 v9, v7
	s_waitcnt vmcnt(0)
	v_mov_b32_e32 v6, v4
	v_mov_b32_e32 v7, v5
	v_mov_b32_e32 v4, v8
	v_mov_b32_e32 v5, v9
	v_lshl_add_u64 v[8:9], s[8:9], 0, v[76:77]
	v_lshl_add_u64 v[8:9], v[74:75], 2, v[8:9]
	global_store_dwordx4 v[8:9], v[64:67], off
	global_store_dwordx4 v[8:9], v[68:71], off offset:16
	s_and_saveexec_b64 s[10:11], vcc
	s_cbranch_execz .LBB0_1143
	global_load_dwordx4 v[10:13], v[72:73], off offset:512 nt
	global_load_dwordx4 v[14:17], v[72:73], off offset:528 nt
	s_waitcnt vmcnt(1)
	v_pk_add_f32 v[2:3], v[2:3], v[12:13]
	v_pk_add_f32 v[0:1], v[0:1], v[10:11]
	s_waitcnt vmcnt(0)
	v_pk_add_f32 v[6:7], v[6:7], v[16:17]
	v_pk_add_f32 v[4:5], v[4:5], v[14:15]
	s_branch .LBB0_1143
